# attention unit setup: second (dead) clearing of the accumulator block removed (30 v_mov_b64 per unit)
# baseline (speedup 1.0000x reference)
; #define LAS __attribute__((address_space(3)))
; __device__ __forceinline__ unsigned cvtpk(float lo, float hi) { f32x2 v = {lo, hi}; bf16x2_t b = __builtin_convertvector(v, bf16x2_t); return __builtin_bit_cast(unsigned, b); }
; __device__ __forceinline__ void attn_unit(const bf16* __restrict__ QB, const bf16* __restrict__ KB, const bf16* __restrict__ VB, bf16* __restrict__ YATT, ...
;     ...
;     u32x4 bexw = {0u, 0u, 0u, 0u}, aex0w = {0u, 0u, 0u, 0u}, aex1w = {0u, 0u, 0u, 0u};
;     if (hi == 0) { bexw.x = cvtpk(s_hi_f, s_lo_f); bexw.y = cvtpk(64.f * s_hi_f, 64.f * s_lo_f); aex0w.x = cvtpk((float)r32, (float)r32); aex1w.x = cvtpk((float)(32 + r32), (float)(32 + r32)); }
;     const bf16x8 bex = __builtin_bit_cast(bf16x8, bexw);
;     const bf16* ksrc[2]; int kdst[2];
; #pragma unroll
;     for (int i = 0; i < 2; ++i) { const int idx = tid + 512 * i, comp = idx >> 9, key = (idx >> 3) & 63, ch = idx & 7; ksrc[i] = Kg + (size_t)key * 512 + comp * 64 + ch * 8; kdst[i] = comp * AK_BYTES + key * AK_STRIDE + ch * 16; }
;     const bf16* vsrc[2]; int vdst[2];
; #pragma unroll
;     for (int i = 0; i < 2; ++i) { const int idx = tid + 512 * i, key = idx >> 4, ch = idx & 15; vsrc[i] = Vg + (size_t)key * 512 + ch * 8; vdst[i] = ((key >> 3) * 4 + (ch >> 2)) * 512 + (key & 7) * 64 + (ch & 3) * 16; }
;     LAS unsigned char* Kl = lds + A_KOFF; LAS unsigned char* Vl = lds + A_VOFF;
;     const int kfo = jc * AK_BYTES + r32 * AK_STRIDE + hi * 16;
;     const int vb = (4 * hi + ((lane & 15) >> 2)) * 64 + ((lane >> 4) & 1) * 32 + (lane & 3) * 8;
;     f32x16 acc[4];
; #pragma unroll
;     for (int e = 0; e < 4; ++e) acc[e] = f32x16{};
;     f32x16 negc = f32x16{};
;     float lrun = 0.f;
;     constexpr float THR = 60.f;
;     u32x4 kreg[2], vreg[2];
;     { const size_t go = (size_t)jstart * 64 * 512; kreg[0] = *(const u32x4*)(ksrc[0] + go); kreg[1] = *(const u32x4*)(ksrc[1] + go); vreg[0] = *(const u32x4*)(vsrc[0] + go); vreg[1] = *(const u32x4*)(vsrc[1] + go); }
;     *(LAS u32x4*)(Kl + kdst[0]) = kreg[0]; *(LAS u32x4*)(Kl + kdst[1]) = kreg[1]; *(LAS u32x4*)(Vl + vdst[0]) = vreg[0]; *(LAS u32x4*)(Vl + vdst[1]) = vreg[1];
;     __syncthreads();
.LBB0_569:
	s_or_b64 exec, exec, s[14:15]
	s_mul_i32 s82, s72, 0x202000
	s_lshl_b64 s[14:15], s[82:83], 1
	s_add_u32 s16, s6, s14
	s_addc_u32 s18, s7, s15
	s_add_u32 s14, s8, s14
	s_addc_u32 s15, s9, s15
	s_lshl_b32 s82, s17, 1
	s_add_u32 s14, s14, s82
	v_bfe_u32 v7, v17, 3, 6
	s_addc_u32 s15, s15, 0
	v_lshlrev_b32_e32 v4, 10, v7
	v_lshlrev_b32_e32 v34, 4, v17
	v_lshl_add_u64 v[2:3], s[14:15], 0, v[4:5]
	v_and_b32_e32 v4, 0x70, v34
	v_lshl_add_u64 v[2:3], v[2:3], 0, v[4:5]
	s_mov_b64 s[14:15], 0xc940000
	v_add_u32_e32 v36, 0x200, v17
	v_lshl_add_u64 v[10:11], v[2:3], 0, s[14:15]
	s_movk_i32 s14, 0x90
	v_ashrrev_i32_e32 v35, 9, v17
	v_ashrrev_i32_e32 v37, 9, v36
	s_add_u32 s16, s16, s82
	v_mad_u32_u24 v7, v7, s14, v4
	v_lshlrev_b32_e32 v2, 6, v35
	v_lshlrev_b32_e32 v8, 6, v37
	v_and_b32_e32 v4, 15, v17
	s_addc_u32 s17, s18, 0
	v_ashrrev_i32_e32 v3, 31, v2
	v_ashrrev_i32_e32 v9, 31, v8
	v_lshlrev_b32_e32 v4, 4, v4
	v_ashrrev_i32_e32 v30, 4, v17
	v_ashrrev_i32_e32 v32, 4, v36
	v_lshl_add_u64 v[20:21], v[2:3], 1, v[10:11]
	v_lshl_add_u64 v[22:23], v[8:9], 1, v[10:11]
	v_lshl_add_u64 v[10:11], s[16:17], 0, v[4:5]
	s_mov_b64 s[14:15], 0xe980000
	v_ashrrev_i32_e32 v31, 31, v30
	v_ashrrev_i32_e32 v33, 31, v32
	v_lshl_add_u64 v[14:15], v[10:11], 0, s[14:15]
	v_lshlrev_b64 v[10:11], 10, v[30:31]
	v_lshlrev_b64 v[12:13], 10, v[32:33]
	v_mov_b32_e32 v179, v5
	v_lshl_add_u64 v[24:25], v[14:15], 0, v[10:11]
	v_lshl_add_u64 v[26:27], v[14:15], 0, v[12:13]
	v_lshlrev_b64 v[14:15], 16, v[178:179]
	v_lshl_add_u64 v[20:21], v[20:21], 0, v[14:15]
	v_lshl_add_u64 v[22:23], v[22:23], 0, v[14:15]
	global_load_dwordx4 v[158:161], v[20:21], off
	global_load_dwordx4 v[162:165], v[22:23], off
	v_lshl_add_u64 v[20:21], v[24:25], 0, v[14:15]
	v_lshl_add_u64 v[22:23], v[26:27], 0, v[14:15]
	global_load_dwordx4 v[166:169], v[20:21], off
	global_load_dwordx4 v[170:173], v[22:23], off
	v_bfe_u32 v31, v17, 2, 2
	v_lshrrev_b32_e32 v33, 5, v17
	v_and_or_b32 v33, v33, s77, v31
	v_lshlrev_b32_e32 v30, 6, v30
	v_lshrrev_b32_e32 v36, 5, v36
	v_and_b32_e32 v34, 48, v34
	v_lshlrev_b32_e32 v33, 9, v33
	v_and_b32_e32 v30, 0x1c0, v30
	v_and_or_b32 v31, v36, s77, v31
	v_lshlrev_b32_e32 v32, 6, v32
	s_load_dwordx2 s[90:91], s[12:13], 0xa0
	s_load_dwordx2 s[88:89], s[10:11], 0xf0
	v_or3_b32 v196, v33, v30, v34
	v_lshlrev_b32_e32 v30, 9, v31
	v_and_b32_e32 v31, 0x1c0, v32
	v_mad_i32_i24 v198, v35, s76, v7
	v_mad_i32_i24 v199, v37, s76, v7
	v_or3_b32 v197, v30, v31, v34
	v_add_u32_e32 v7, 0, v198
	v_add_u32_e32 v32, 0, v199
	v_add_u32_e32 v30, 0, v196
	v_add_u32_e32 v31, 0, v197
	v_mov_b32_e32 v33, v5
	v_lshlrev_b32_e32 v179, 2, v18
	v_mov_b32_e32 v18, v5
	v_mov_b32_e32 v19, v5
	v_mov_b32_e32 v20, v5
	v_mov_b32_e32 v21, v5
	v_mov_b32_e32 v22, v5
	v_mov_b32_e32 v23, v5
	v_mov_b32_e32 v24, v5
	v_mov_b32_e32 v25, v5
	v_mov_b32_e32 v26, v5
	v_mov_b32_e32 v27, v5
	v_mov_b32_e32 v28, v5
	v_mov_b32_e32 v29, v5
	s_add_i32 s10, s80, 31
	v_cmp_gt_u32_e32 vcc, s39, v178
	s_ashr_i32 s73, s10, 6
	s_waitcnt vmcnt(3)
	ds_write_b128 v7, v[158:161]
	s_waitcnt vmcnt(2)
	ds_write_b128 v32, v[162:165]
	s_waitcnt vmcnt(1)
	ds_write_b128 v30, v[166:169] offset:36864
	s_waitcnt vmcnt(0)
	ds_write_b128 v31, v[170:173] offset:36864
	v_mov_b32_e32 v32, v5
	v_mov_b32_e32 v30, v5
	v_mov_b32_e32 v31, v5
	v_mov_b64_e32 v[48:49], v[32:33]
	v_mov_b64_e32 v[64:65], v[32:33]
	v_mov_b64_e32 v[80:81], v[32:33]
	v_mov_b64_e32 v[46:47], v[30:31]
	v_mov_b64_e32 v[44:45], v[28:29]
	v_mov_b64_e32 v[42:43], v[26:27]
	v_mov_b64_e32 v[40:41], v[24:25]
	v_mov_b64_e32 v[38:39], v[22:23]
	v_mov_b64_e32 v[36:37], v[20:21]
	v_mov_b64_e32 v[34:35], v[18:19]
	v_mov_b64_e32 v[62:63], v[30:31]
	v_mov_b64_e32 v[60:61], v[28:29]
	v_mov_b64_e32 v[58:59], v[26:27]
	v_mov_b64_e32 v[56:57], v[24:25]
	v_mov_b64_e32 v[54:55], v[22:23]
	v_mov_b64_e32 v[52:53], v[20:21]
	v_mov_b64_e32 v[50:51], v[18:19]
	v_mov_b64_e32 v[78:79], v[30:31]
	v_mov_b64_e32 v[76:77], v[28:29]
	v_mov_b64_e32 v[74:75], v[26:27]
	v_mov_b64_e32 v[72:73], v[24:25]
	v_mov_b64_e32 v[70:71], v[22:23]
	v_mov_b64_e32 v[68:69], v[20:21]
	v_mov_b64_e32 v[66:67], v[18:19]
	s_waitcnt lgkmcnt(0)
	s_barrier
	s_and_saveexec_b64 s[92:93], vcc
	s_cbranch_execz .LBB0_583
	v_lshrrev_b32_e32 v18, 2, v17
	s_mul_i32 s10, s38, 0x2400
	v_mul_u32_u24_e32 v7, 0x90, v83
	v_and_or_b32 v18, v18, 3, v179
	v_lshlrev_b32_e32 v19, 1, v17
	v_lshlrev_b32_e32 v20, 3, v17
	s_add_i32 s10, s10, 0
	v_and_b32_e32 v19, 32, v19
	v_and_b32_e32 v20, 24, v20
	v_add3_u32 v200, s10, v7, v6
	v_lshl_add_u32 v6, v18, 6, 0
	v_add3_u32 v201, v6, v19, v20
	v_sub_u32_e32 v6, s80, v16
	v_max_i32_e32 v6, 0, v6
	v_lshrrev_b32_e32 v202, 6, v6
	s_ashr_i32 s10, s80, 6
	v_sub_u32_e32 v6, v82, v179
	v_lshlrev_b32_e32 v7, 6, v178
	v_subrev_u32_e32 v203, s10, v178
	v_sub_u32_e32 v204, v6, v7
	v_or_b32_e32 v205, 63, v7
	v_mad_u64_u32 v[6:7], s[10:11], s72, v188, v[14:15]
	v_lshlrev_b32_e32 v14, 7, v17
	v_and_b32_e32 v14, 0xfc00, v14
	v_mov_b32_e32 v15, v5
	v_lshl_add_u64 v[14:15], v[6:7], 0, v[14:15]
	v_and_b32_e32 v16, 7, v17
	s_add_u32 s8, s8, 0xc950000
	v_lshl_or_b32 v14, v16, 4, v14
	s_addc_u32 s9, s9, 0
	v_lshl_add_u64 v[2:3], v[2:3], 1, v[14:15]
	v_lshl_add_u64 v[180:181], s[8:9], 0, v[2:3]
	v_lshl_add_u64 v[2:3], v[8:9], 1, v[14:15]
	v_lshl_add_u64 v[182:183], s[8:9], 0, v[2:3]
	s_add_u32 s6, s6, 0xe990000
	v_lshl_add_u64 v[2:3], v[6:7], 0, v[10:11]
	s_addc_u32 s7, s7, 0
	v_lshl_add_u64 v[2:3], v[2:3], 0, v[4:5]
	v_lshl_add_u64 v[184:185], s[6:7], 0, v[2:3]
	v_lshl_add_u64 v[2:3], v[6:7], 0, v[12:13]
	v_lshl_add_u64 v[2:3], v[2:3], 0, v[4:5]
	v_mov_b32_e32 v16, v5
	v_mov_b32_e32 v17, v5
	v_lshl_add_u64 v[186:187], s[6:7], 0, v[2:3]
	s_nop 0
	v_readfirstlane_b32 s98, v180
	v_readfirstlane_b32 s99, v181
	v_readfirstlane_b32 s100, v184
	v_readfirstlane_b32 s101, v185
	s_nop 3
	v_subrev_u32_e32 v180, s98, v180
	v_subrev_u32_e32 v182, s98, v182
	v_subrev_u32_e32 v184, s100, v184
	v_subrev_u32_e32 v186, s100, v186
	s_add_u32 s98, s98, s82
	s_addc_u32 s99, s99, s83
	s_add_u32 s100, s100, s82
	s_addc_u32 s101, s101, s83
	v_mov_b32_e32 v2, v5
	v_mov_b32_e32 v3, v5
	v_mov_b32_e32 v4, v5
	v_mov_b32_e32 v6, v5
	v_mov_b32_e32 v7, v5
	v_mov_b32_e32 v8, v5
	v_mov_b32_e32 v9, v5
	v_mov_b32_e32 v10, v5
	v_mov_b32_e32 v11, v5
	v_mov_b32_e32 v12, v5
	v_mov_b32_e32 v13, v5
	v_mov_b32_e32 v14, v5
	v_mov_b32_e32 v15, v5
	v_mov_b64_e32 v[96:97], v[16:17]
	s_mov_b32 s81, 0
	v_sub_u32_e32 v206, v202, v178
	v_mov_b32_e32 v207, 0
	s_mov_b64 s[94:95], 0
	v_mov_b64_e32 v[20:21], v[4:5]
	v_mov_b64_e32 v[18:19], v[2:3]
	v_mov_b64_e32 v[94:95], v[14:15]
	v_mov_b64_e32 v[92:93], v[12:13]
	v_mov_b64_e32 v[90:91], v[10:11]
	v_mov_b64_e32 v[88:89], v[8:9]
	v_mov_b64_e32 v[86:87], v[6:7]
	v_mov_b64_e32 v[84:85], v[4:5]
	v_mov_b64_e32 v[82:83], v[2:3]
	s_branch .LBB0_572
